# P1 rmsnorm pre-pass: next iteration's two rows touched while the current rows are reduced and stored
# speedup vs baseline: 1.0014x; 1.0014x over previous
.LBB0_107:
	s_add_i32 s8, s4, s72
	s_cmpk_lt_i32 s8, 0x4000
	s_cselect_b32 s42, s8, s4
	s_ashr_i32 s5, s4, 31
	s_lshl_b64 s[6:7], s[4:5], 12
	s_ashr_i32 s43, s42, 31
	v_lshl_add_u64 v[22:23], v[0:1], 0, s[6:7]
	s_lshl_b64 s[6:7], s[42:43], 12
	s_waitcnt lgkmcnt(0)
	global_load_dwordx4 v[10:13], v[22:23], off
	global_load_dwordx4 v[14:17], v[22:23], off offset:1024
	global_load_dwordx4 v[18:21], v[22:23], off offset:2048
	s_nop 0
	global_load_dwordx4 v[22:25], v[22:23], off offset:3072
	v_lshl_add_u64 v[38:39], v[0:1], 0, s[6:7]
	global_load_dwordx4 v[26:29], v[38:39], off
	global_load_dwordx4 v[30:33], v[38:39], off offset:1024
	global_load_dwordx4 v[34:37], v[38:39], off offset:2048
	s_nop 0
	global_load_dwordx4 v[38:41], v[38:39], off offset:3072
	s_lshl_b32 s98, s72, 1
	s_add_i32 s98, s98, s4
	s_cmpk_lt_i32 s98, 0x4000
	s_cselect_b32 s98, s98, s4
	s_lshl_b32 s100, s98, 12
	s_mov_b32 s101, 0
	v_lshl_add_u64 v[80:81], v[0:1], 0, s[100:101]
	global_load_dwordx4 v[84:87], v[80:81], off
	global_load_dwordx4 v[88:91], v[80:81], off offset:1024
	global_load_dwordx4 v[92:95], v[80:81], off offset:2048
	global_load_dwordx4 v[96:99], v[80:81], off offset:3072
	s_lshl_b32 s98, s72, 1
	s_add_i32 s98, s98, s42
	s_cmpk_lt_i32 s98, 0x4000
	s_cselect_b32 s98, s98, s42
	s_lshl_b32 s100, s98, 12
	s_mov_b32 s101, 0
	v_lshl_add_u64 v[80:81], v[0:1], 0, s[100:101]
	global_load_dwordx4 v[100:103], v[80:81], off
	global_load_dwordx4 v[104:107], v[80:81], off offset:1024
	global_load_dwordx4 v[108:111], v[80:81], off offset:2048
	global_load_dwordx4 v[112:115], v[80:81], off offset:3072
	s_lshl_b64 s[6:7], s[4:5], 11
	v_lshl_add_u64 v[42:43], v[2:3], 0, s[6:7]
	s_lshl_b64 s[6:7], s[42:43], 11
	v_lshl_add_u64 v[44:45], v[2:3], 0, s[6:7]
	s_waitcnt vmcnt(15)
	v_mul_f32_e32 v54, v13, v13
	s_waitcnt vmcnt(14)
	v_mul_f32_e32 v55, v15, v15
	v_mul_f32_e32 v53, v11, v11
	v_mul_f32_e32 v56, v17, v17
	v_cvt_pk_bf16_f32 v46, v10, v11
	v_cvt_pk_bf16_f32 v47, v12, v13
	v_cvt_pk_bf16_f32 v48, v14, v15
	v_fmac_f32_e32 v54, v12, v12
	s_waitcnt vmcnt(11)
	v_mul_f32_e32 v11, v27, v27
	v_mul_f32_e32 v12, v29, v29
	v_fmac_f32_e32 v55, v14, v14
	s_waitcnt vmcnt(10)
	v_mul_f32_e32 v13, v31, v31
	v_mul_f32_e32 v14, v33, v33
	v_mul_f32_e32 v57, v19, v19
	v_mul_f32_e32 v58, v21, v21
	v_cvt_pk_bf16_f32 v49, v16, v17
	v_fmac_f32_e32 v53, v10, v10
	v_fmac_f32_e32 v56, v16, v16
	s_waitcnt vmcnt(9)
	v_mul_f32_e32 v15, v35, v35
	v_mul_f32_e32 v16, v37, v37
	v_fmac_f32_e32 v11, v26, v26
	v_fmac_f32_e32 v12, v28, v28
	v_fmac_f32_e32 v13, v30, v30
	v_fmac_f32_e32 v14, v32, v32
	v_mul_f32_e32 v59, v23, v23
	v_mul_f32_e32 v60, v25, v25
	v_cvt_pk_bf16_f32 v50, v18, v19
	v_cvt_pk_bf16_f32 v51, v20, v21
	v_fmac_f32_e32 v57, v18, v18
	v_fmac_f32_e32 v58, v20, v20
	s_waitcnt vmcnt(8)
	v_mul_f32_e32 v17, v39, v39
	v_mul_f32_e32 v18, v41, v41
	v_add_f32_e32 v19, v53, v54
	v_add_f32_e32 v20, v55, v56
	v_fmac_f32_e32 v15, v34, v34
	v_fmac_f32_e32 v16, v36, v36
	v_add_f32_e32 v11, v11, v12
	v_add_f32_e32 v13, v13, v14
	v_fmac_f32_e32 v59, v22, v22
	v_fmac_f32_e32 v60, v24, v24
	v_add_f32_e32 v21, v57, v58
	v_fmac_f32_e32 v17, v38, v38
	v_fmac_f32_e32 v18, v40, v40
	v_add_f32_e32 v12, v19, v20
	v_add_f32_e32 v14, v15, v16
	v_add_f32_e32 v11, v11, v13
	v_cvt_pk_bf16_f32 v52, v22, v23
	v_add_f32_e32 v22, v59, v60
	v_add_f32_e32 v15, v17, v18
	v_add_f32_e32 v12, v12, v21
	v_add_f32_e32 v11, v11, v14
	v_add_f32_e32 v12, v12, v22
	v_add_f32_e32 v14, v11, v15
	ds_bpermute_b32 v13, v4, v12
	ds_bpermute_b32 v15, v4, v14
	v_cvt_pk_bf16_f32 v10, v26, v27
	v_cvt_pk_bf16_f32 v11, v28, v29
	global_store_dwordx2 v[42:43], v[46:47], off
	s_waitcnt lgkmcnt(1)
	v_add_f32_e32 v16, v12, v13
	s_waitcnt lgkmcnt(0)
	v_add_f32_e32 v14, v14, v15
	ds_bpermute_b32 v17, v5, v16
	ds_bpermute_b32 v15, v5, v14
	global_store_dwordx2 v[44:45], v[10:11], off
	v_cvt_pk_bf16_f32 v12, v30, v31
	v_cvt_pk_bf16_f32 v13, v32, v33
	s_waitcnt lgkmcnt(1)
	v_add_f32_e32 v16, v16, v17
	s_waitcnt lgkmcnt(0)
	v_add_f32_e32 v15, v14, v15
	ds_bpermute_b32 v17, v6, v16
	ds_bpermute_b32 v18, v6, v15
	global_store_dwordx2 v[42:43], v[48:49], off offset:512
	global_store_dwordx2 v[42:43], v[50:51], off offset:1024
	v_cvt_pk_bf16_f32 v14, v34, v35
	s_waitcnt lgkmcnt(1)
	v_add_f32_e32 v16, v16, v17
	s_waitcnt lgkmcnt(0)
	v_add_f32_e32 v18, v15, v18
	ds_bpermute_b32 v17, v7, v16
	ds_bpermute_b32 v19, v7, v18
	v_cvt_pk_bf16_f32 v15, v36, v37
	global_store_dwordx2 v[44:45], v[12:13], off offset:512
	global_store_dwordx2 v[44:45], v[14:15], off offset:1024
	v_cvt_pk_bf16_f32 v53, v24, v25
	s_waitcnt lgkmcnt(1)
	v_add_f32_e32 v10, v16, v17
	s_waitcnt lgkmcnt(0)
	v_add_f32_e32 v16, v18, v19
	ds_bpermute_b32 v11, v8, v10
	ds_bpermute_b32 v17, v8, v16
	v_cvt_pk_bf16_f32 v14, v38, v39
	v_cvt_pk_bf16_f32 v15, v40, v41
	global_store_dwordx2 v[42:43], v[52:53], off offset:1536
	s_waitcnt lgkmcnt(1)
	v_add_f32_e32 v10, v10, v11
	s_waitcnt lgkmcnt(0)
	v_add_f32_e32 v12, v16, v17
	ds_bpermute_b32 v11, v9, v10
	ds_bpermute_b32 v13, v9, v12
	global_store_dwordx2 v[44:45], v[14:15], off offset:1536
	s_and_saveexec_b64 s[6:7], s[0:1]
	s_cbranch_execz .LBB0_106
	s_waitcnt lgkmcnt(0)
	v_add_f32_e32 v12, v12, v13
	v_fmamk_f32 v12, v12, 0x3a800000, v211
	s_mov_b32 s3, 0xf800000
	v_mul_f32_e32 v13, 0x4f800000, v12
	v_cmp_gt_f32_e32 vcc, s3, v12
	v_add_f32_e32 v10, v10, v11
	v_fmamk_f32 v10, v10, 0x3a800000, v211
	v_cndmask_b32_e32 v12, v12, v13, vcc
	v_sqrt_f32_e32 v13, v12
	v_mul_f32_e32 v11, 0x4f800000, v10
	v_readlane_b32 s10, v250, 53
	v_readlane_b32 s11, v250, 54
	v_add_u32_e32 v14, -1, v13
	v_add_u32_e32 v15, 1, v13
	v_fma_f32 v16, -v14, v13, v12
	v_fma_f32 v17, -v15, v13, v12
	v_cmp_ge_f32_e64 s[38:39], 0, v16
	s_nop 1
	v_cndmask_b32_e64 v13, v13, v14, s[38:39]
	v_cmp_lt_f32_e64 s[38:39], 0, v17
	s_nop 1
	v_cndmask_b32_e64 v13, v13, v15, s[38:39]
	v_mul_f32_e32 v14, 0x37800000, v13
	v_cndmask_b32_e32 v13, v13, v14, vcc
	v_cmp_class_f32_e32 vcc, v12, v212
	v_cmp_gt_f32_e64 s[38:39], s3, v10
	s_nop 0
	v_cndmask_b32_e32 v12, v13, v12, vcc
	v_div_scale_f32 v13, s[18:19], v12, v12, 1.0
	v_rcp_f32_e32 v14, v13
	v_cndmask_b32_e64 v10, v10, v11, s[38:39]
	v_sqrt_f32_e32 v11, v10
	v_fma_f32 v15, -v13, v14, 1.0
	v_fmac_f32_e32 v14, v15, v14
	v_div_scale_f32 v15, vcc, 1.0, v12, 1.0
	v_mul_f32_e32 v16, v15, v14
	v_fma_f32 v17, -v13, v16, v15
	v_fmac_f32_e32 v16, v17, v14
	v_fma_f32 v13, -v13, v16, v15
	v_add_u32_e32 v15, -1, v11
	v_fma_f32 v17, -v15, v11, v10
	v_cmp_ge_f32_e64 s[40:41], 0, v17
	v_add_u32_e32 v17, 1, v11
	v_div_fmas_f32 v13, v13, v14, v16
	v_cndmask_b32_e64 v15, v11, v15, s[40:41]
	v_fma_f32 v11, -v17, v11, v10
	v_cmp_lt_f32_e64 s[40:41], 0, v11
	v_div_fixup_f32 v12, v13, v12, 1.0
	s_nop 0
	v_cndmask_b32_e64 v11, v15, v17, s[40:41]
	v_mul_f32_e32 v15, 0x37800000, v11
	v_cndmask_b32_e64 v11, v11, v15, s[38:39]
	v_cmp_class_f32_e64 s[38:39], v10, v212
	s_nop 1
	v_cndmask_b32_e64 v10, v11, v10, s[38:39]
	v_div_scale_f32 v11, s[18:19], v10, v10, 1.0
	v_rcp_f32_e32 v15, v11
	s_lshl_b64 s[18:19], s[42:43], 2
	s_add_u32 s18, s10, s18
	s_addc_u32 s19, s11, s19
	v_fma_f32 v13, -v11, v15, 1.0
	v_fmac_f32_e32 v15, v13, v15
	v_div_scale_f32 v13, vcc, 1.0, v10, 1.0
	v_mul_f32_e32 v14, v13, v15
	v_fma_f32 v16, -v11, v14, v13
	v_fmac_f32_e32 v14, v16, v15
	v_fma_f32 v11, -v11, v14, v13
	s_lshl_b64 s[4:5], s[4:5], 2
	v_div_fmas_f32 v11, v11, v15, v14
	s_add_u32 s4, s10, s4
	v_div_fixup_f32 v10, v11, v10, 1.0
	s_addc_u32 s5, s11, s5
	global_store_dword v65, v10, s[4:5]
	global_store_dword v65, v12, s[18:19]
	s_branch .LBB0_106
